# scan step c: segment carry chain with its 7 LDS reads issued together (early exits per wave), added to scan-b, wide partial stores and barrier sink
# speedup vs baseline: 1.0029x; 1.0002x over previous
.LBB0_1008:
	ds_read_b64 v[106:107], v100
	ds_read_b64 v[108:109], v100 offset:512
	ds_read_b64 v[110:111], v100 offset:1024
	ds_read_b64 v[112:113], v100 offset:1536
	ds_read_b64 v[114:115], v100 offset:2048
	ds_read_b64 v[116:117], v100 offset:2560
	ds_read_b64 v[118:119], v100 offset:3072
	s_waitcnt lgkmcnt(6)
	v_pk_fma_f32 v[102:103], v[192:193], v[98:99], v[106:107] op_sel:[0,1,0] op_sel_hi:[1,0,1]
	s_nop 0
	v_pk_fma_f32 v[98:99], v[194:195], v[98:99], v[102:103]
	s_cmp_eq_u32 s2, 1
	s_cbranch_scc1 .Lscanc_done
	s_waitcnt lgkmcnt(5)
	v_pk_fma_f32 v[102:103], v[192:193], v[98:99], v[108:109] op_sel:[0,1,0] op_sel_hi:[1,0,1]
	s_nop 0
	v_pk_fma_f32 v[98:99], v[194:195], v[98:99], v[102:103]
	s_cmp_eq_u32 s2, 2
	s_cbranch_scc1 .Lscanc_done
	s_waitcnt lgkmcnt(4)
	v_pk_fma_f32 v[102:103], v[192:193], v[98:99], v[110:111] op_sel:[0,1,0] op_sel_hi:[1,0,1]
	s_nop 0
	v_pk_fma_f32 v[98:99], v[194:195], v[98:99], v[102:103]
	s_cmp_eq_u32 s2, 3
	s_cbranch_scc1 .Lscanc_done
	s_waitcnt lgkmcnt(3)
	v_pk_fma_f32 v[102:103], v[192:193], v[98:99], v[112:113] op_sel:[0,1,0] op_sel_hi:[1,0,1]
	s_nop 0
	v_pk_fma_f32 v[98:99], v[194:195], v[98:99], v[102:103]
	s_cmp_eq_u32 s2, 4
	s_cbranch_scc1 .Lscanc_done
	s_waitcnt lgkmcnt(2)
	v_pk_fma_f32 v[102:103], v[192:193], v[98:99], v[114:115] op_sel:[0,1,0] op_sel_hi:[1,0,1]
	s_nop 0
	v_pk_fma_f32 v[98:99], v[194:195], v[98:99], v[102:103]
	s_cmp_eq_u32 s2, 5
	s_cbranch_scc1 .Lscanc_done
	s_waitcnt lgkmcnt(1)
	v_pk_fma_f32 v[102:103], v[192:193], v[98:99], v[116:117] op_sel:[0,1,0] op_sel_hi:[1,0,1]
	s_nop 0
	v_pk_fma_f32 v[98:99], v[194:195], v[98:99], v[102:103]
	s_cmp_eq_u32 s2, 6
	s_cbranch_scc1 .Lscanc_done
	s_waitcnt lgkmcnt(0)
	v_pk_fma_f32 v[102:103], v[192:193], v[98:99], v[118:119] op_sel:[0,1,0] op_sel_hi:[1,0,1]
	s_nop 0
	v_pk_fma_f32 v[98:99], v[194:195], v[98:99], v[102:103]
.Lscanc_done:
.LBB0_1009:
	s_waitcnt lgkmcnt(0)
	v_pk_fma_f32 v[96:97], v[190:191], v[98:99], v[96:97]
	s_mul_i32 s2, s31, 0x880
	v_pk_fma_f32 v[96:97], v[188:189], v[98:99], v[96:97] op_sel:[0,1,0] op_sel_hi:[1,0,1]
	v_cvt_pk_bf16_f32 v100, v98, v169
	v_add_u32_e32 v101, s2, v217
	v_pk_fma_f32 v[94:95], v[190:191], v[96:97], v[94:95] op_sel:[0,1,0] op_sel_hi:[1,0,1]
	ds_write_b16 v101, v100
	v_pk_fma_f32 v[94:95], v[188:189], v[96:97], v[94:95]
	v_cvt_pk_bf16_f32 v100, v99, v169
	s_mulk_i32 s39, 0x110
	v_pk_fma_f32 v[92:93], v[190:191], v[94:95], v[92:93] op_sel:[0,1,0] op_sel_hi:[1,0,1]
	ds_write_b16 v101, v100 offset:128
	v_pk_fma_f32 v[92:93], v[188:189], v[94:95], v[92:93]
	v_add_u32_e32 v100, s39, v217
	v_pk_fma_f32 v[90:91], v[190:191], v[92:93], v[90:91] op_sel:[0,1,0] op_sel_hi:[1,0,1]
	v_cvt_pk_bf16_f32 v98, v97, v169
	ds_write_b16 v100, v98
	v_pk_fma_f32 v[90:91], v[188:189], v[92:93], v[90:91]
	v_cvt_pk_bf16_f32 v98, v96, v169
	ds_write_b16 v100, v98 offset:128
	v_cvt_pk_bf16_f32 v96, v95, v169
	v_pk_fma_f32 v[88:89], v[190:191], v[90:91], v[88:89] op_sel:[0,1,0] op_sel_hi:[1,0,1]
	ds_write_b16 v100, v96 offset:272
	v_cvt_pk_bf16_f32 v96, v94, v169
	ds_write_b16 v100, v96 offset:400
	v_cvt_pk_bf16_f32 v94, v93, v169
	v_pk_fma_f32 v[88:89], v[188:189], v[90:91], v[88:89]
	ds_write_b16 v100, v94 offset:544
	v_cvt_pk_bf16_f32 v94, v92, v169
	ds_write_b16 v100, v94 offset:672
	v_cvt_pk_bf16_f32 v92, v91, v169
	v_pk_fma_f32 v[86:87], v[190:191], v[88:89], v[86:87] op_sel:[0,1,0] op_sel_hi:[1,0,1]
	ds_write_b16 v100, v92 offset:816
	v_cvt_pk_bf16_f32 v92, v90, v169
	ds_write_b16 v100, v92 offset:944
	v_cvt_pk_bf16_f32 v90, v89, v169
	v_pk_fma_f32 v[86:87], v[188:189], v[88:89], v[86:87]
	s_xor_b32 s38, s38, 1
	ds_write_b16 v100, v90 offset:1088
	v_cvt_pk_bf16_f32 v90, v88, v169
	ds_write_b16 v100, v90 offset:1216
	v_cvt_pk_bf16_f32 v88, v87, v169
	v_pk_fma_f32 v[84:85], v[190:191], v[86:87], v[84:85] op_sel:[0,1,0] op_sel_hi:[1,0,1]
	ds_write_b16 v100, v88 offset:1360
	v_cvt_pk_bf16_f32 v88, v86, v169
	ds_write_b16 v100, v88 offset:1488
	v_pk_fma_f32 v[84:85], v[188:189], v[86:87], v[84:85]
	s_cmp_eq_u32 s31, 7
	v_cvt_pk_bf16_f32 v86, v85, v169
	ds_write_b16 v100, v86 offset:1632
	v_cvt_pk_bf16_f32 v86, v84, v169
	ds_write_b16 v100, v86 offset:1760
	s_cbranch_scc0 .LBB0_1012
	v_pk_fma_f32 v[82:83], v[190:191], v[84:85], v[82:83] op_sel:[0,1,0] op_sel_hi:[1,0,1]
	v_lshl_add_u32 v86, s38, 9, v212
	v_pk_fma_f32 v[82:83], v[188:189], v[84:85], v[82:83]
	s_andn2_b64 vcc, exec, s[6:7]
	v_pk_mov_b32 v[84:85], v[82:83], v[82:83] op_sel:[1,0]
	ds_write_b64 v86, v[84:85]
	s_cbranch_vccnz .LBB0_1012
	global_store_dword v[182:183], v83, off
	global_store_dword v[184:185], v82, off
